# attention work-queue order changed: the two long single-wave units first, two GQA units moved between the diff units so the delayed workgroups re-synchronise (makespan balancing)
# speedup vs baseline: 1.0058x; 1.0058x over previous
; __device__ __forceinline__ int ltid() { int t = threadIdx.x; asm volatile("" : "+v"(t)); return t; }
; __global__ void __launch_bounds__(NWAVES * 64) fwd_kernel(Args args) {
;     ...
;                     if (ltid() == 0) misc[0] = (int)atomicAdd(ctl + CW_CNT + 64 * (queue + 8 * (pi & 1)), 1u);
;                     __syncthreads();
;                     const int ui = misc[0]; if (ui >= QUNITS) break;
;                     int seq, head, qb;
;                     bool virt = false;
;                     if (ui < 64) { seq = 4; head = queue; qb = ui; } else if (ui < 128) { seq = 4; head = 8 + queue; qb = ui - 64; }
;                     else if (ui == 128) { seq = 4; head = queue; qb = 64; virt = true; } else if (ui == 129) { seq = 4; head = 8 + queue; qb = 64; }
;                     else if (ui < 162) { const int j = ui - 130; seq = j >> 3; qb = j & 7; head = queue; } else if (ui < 166) { seq = ui - 162; qb = 8; head = queue; virt = true; }
;                     else { const int j = ui - 166; seq = j / 9; qb = j % 9; head = 8 + queue; }
.LBB0_39:
	s_or_b64 exec, exec, s[0:1]
	v_mov_b32_e32 v0, s75
	s_waitcnt lgkmcnt(0)
	s_barrier
	ds_read_b32 v0, v0
	s_movk_i32 s0, 0xc9
	s_waitcnt lgkmcnt(0)
	v_cmp_lt_i32_e32 vcc, s0, v0
	v_readfirstlane_b32 s22, v0
	s_mov_b64 s[0:1], -1
	s_cbranch_vccnz .LBB0_36
	s_cmp_lt_u32 s22, 130
	s_cbranch_scc0 .Lrm_done
	s_cmp_lt_u32 s22, 68
	s_cbranch_scc1 .Lrm_1
	s_sub_i32 s22, s22, 2
	s_branch .Lrm_done
.Lrm_1:
	s_cmp_lt_u32 s22, 34
	s_cbranch_scc1 .Lrm_2
	s_sub_i32 s22, s22, 4
	s_branch .Lrm_done
.Lrm_2:
	s_cmp_lt_u32 s22, 32
	s_cbranch_scc1 .Lrm_3
	s_add_i32 s22, s22, 32
	s_branch .Lrm_done
.Lrm_3:
	s_cmp_lt_u32 s22, 2
	s_cbranch_scc1 .Lrm_4
	s_sub_i32 s22, s22, 2
	s_branch .Lrm_done
.Lrm_4:
	s_add_i32 s22, s22, 128
.Lrm_done:
	s_mov_b32 s4, 4
	s_cmp_lt_i32 s22, 64
	s_mov_b64 s[28:29], 0
	s_cbranch_scc1 .LBB0_54
	s_cmpk_gt_u32 s22, 0x7f
	s_mov_b64 s[2:3], -1
	s_cbranch_scc0 .LBB0_58
	s_cmpk_lt_i32 s22, 0x81
	s_cbranch_scc1 .LBB0_55
	s_cmpk_lg_i32 s22, 0x81
	s_cbranch_scc0 .LBB0_52
	s_cmpk_gt_u32 s22, 0xa1
	s_cbranch_scc0 .LBB0_49
	s_cmpk_gt_u32 s22, 0xa5
	s_mov_b64 s[0:1], -1
	s_cbranch_scc0 .LBB0_47
	s_add_i32 s0, s22, 0x5a
	s_and_b32 s1, s0, 0xff
	s_mul_i32 s1, s1, 57
	s_bfe_u32 s4, s1, 0x70009
	s_mul_i32 s1, s4, 9
	s_sub_i32 s0, s0, s1
	s_and_b32 s5, s0, 0xff
	s_mov_b64 s[0:1], 0
